# L1: K-loop body moved +32 bytes (loop head region at 8 mod 64 like the microbenchmark base), code behind the loop kept at its address mod 64; on top of K1+R1
# baseline (speedup 1.0000x reference)
; #define PG8_STAGE(bufoff, gbase, voff) do { _Pragma("unroll") for (int _i = 0; _i < 2; ++_i) { unsigned _vo = (voff)[_i]; asm volatile("" : "+v"(_vo));   \
;         __builtin_amdgcn_global_load_lds((const unsigned*)((const char*)(gbase) + _vo), (LAS unsigned*)(lds + (bufoff) + ldsw + _i * 8192), 16, 0, 0); } } while (0)
; #define PG8_LDA(dst, b, h) do { _Pragma("unroll") for (int m = 0; m < 4; ++m) _Pragma("unroll") for (int k = 0; k < 2; ++k) dst[m][k] = *(const LAS bf16x8*)(lds + PG8_SA(b, h) + aoff + m * 2048 + k * 1024); } while (0)
; #define PG8_LDB(dst, b, h) do { _Pragma("unroll") for (int n = 0; n < 2; ++n) _Pragma("unroll") for (int k = 0; k < 2; ++k) dst[n][k] = *(const LAS bf16x8*)(lds + PG8_SB(b, h) + boff + n * 2048 + k * 1024); } while (0)
; #define PG8_MMA(ai, bj, At, Bt) do { __builtin_amdgcn_s_setprio(1); _Pragma("unroll") for (int m = 0; m < 4; ++m) _Pragma("unroll") for (int n = 0; n < 2; ++n) _Pragma("unroll") for (int k = 0; k < 2; ++k) \
;         acc[ai][bj][m][n] = __builtin_amdgcn_mfma_f32_16x16x32_bf16(Bt[n][k], At[m][k], acc[ai][bj][m][n], 0, 0, 0); __builtin_amdgcn_s_setprio(0); } while (0)
; #define PG8_WAIT_V(n) asm volatile("s_waitcnt vmcnt(" #n ")" ::: "memory")
; #define PG8_WAIT_L(n) asm volatile("s_waitcnt lgkmcnt(" #n ")" ::: "memory")
; #define PG8_BAR __builtin_amdgcn_s_barrier()
; __device__ __forceinline__ void gemm_phase(LAS unsigned char* lds, const Call& C, const int tid, const Args& args) {
;     ...
;         const int nt = 2 * cur.np;
;         for (int t = 0; t < nt; t += 2) {
;             const bool last = (t == nt - 2);
;             const char* a1 = cA + (size_t)(t + 1) * kstep;
;             const char* a2 = last ? nA : cA + (size_t)(t + 2) * kstep; const char* b2 = last ? nB : cB + (size_t)(t + 2) * kstep;
;             const char* a3 = a2 + kstep; const char* b3 = b2 + kstep;
;             PG8_LDB(B0, 0, 0); PG8_LDB(B1, 0, 1); PG8_SCHED; PG8_LDA(At, 0, 0); PG8_STAGE(PG8_SA(1, 1), a1 + hstepA, voffA);
;             PG8_WAIT_V(8); PG8_WAIT_L(0); PG8_BAR; PG8_MMA(0, 0, At, B0); PG8_MMA(0, 1, At, B1); PG8_BAR; PG8_SCHED;
;             PG8_LDA(At, 0, 1); PG8_STAGE(PG8_SB(0, 0), b2, voffB); PG8_STAGE(PG8_SB(0, 1), b2 + hstepB, voffB); PG8_STAGE(PG8_SA(0, 0), a2, voffA);
;             PG8_WAIT_V(8); PG8_WAIT_L(0); PG8_BAR; PG8_MMA(1, 0, At, B0); PG8_MMA(1, 1, At, B1); PG8_BAR; PG8_SCHED;
.Lnu_noprod:
	s_cmp_eq_u32 s16, 0
	s_cbranch_scc1 .LBB0_313
	s_lshl_b32 s12, s16, 1
	s_add_i32 s13, s12, -2
	s_add_u32 s16, s8, 0x100
	s_addc_u32 s17, s9, 0
	s_mov_b32 s24, 0
	s_waitcnt lgkmcnt(0)
	s_add_i32 s25, s24, 2
	s_add_u32 s8, s0, 0x100
	s_addc_u32 s9, s1, 0
	s_add_i32 s34, 0, 0x10000
	s_cmp_eq_u32 s13, s24
	s_cselect_b32 s39, s87, s9
	s_cselect_b32 s38, s86, s8
	v_add_u32_e32 v80, s34, v245
	s_cselect_b32 s41, s49, s17
	s_cselect_b32 s40, s48, s16
	s_add_i32 s24, 0, 0x14000
	ds_read_b128 v[136:139], v80
	ds_read_b128 v[140:143], v80 offset:1024
	ds_read_b128 v[144:147], v80 offset:2048
	ds_read_b128 v[148:151], v80 offset:3072
	v_add_u32_e32 v80, s24, v245
	ds_read_b128 v[152:155], v80
	ds_read_b128 v[156:159], v80 offset:1024
	ds_read_b128 v[160:163], v80 offset:2048
	ds_read_b128 v[164:167], v80 offset:3072
	v_mov_b32_e32 v80, v205
	s_add_u32 s0, s0, s89
	ds_read_b128 v[168:171], v246
	ds_read_b128 v[172:175], v246 offset:1024
	ds_read_b128 v[176:179], v246 offset:2048
	ds_read_b128 v[180:183], v246 offset:3072
	ds_read_b128 v[184:187], v246 offset:4096
	ds_read_b128 v[188:191], v246 offset:5120
	ds_read_b128 v[192:195], v246 offset:6144
	ds_read_b128 v[196:199], v246 offset:7168
	s_addc_u32 s1, s1, s94
	s_add_i32 m0, s20, 0xc000
	s_nop 0
	global_load_lds_dwordx4 v80, s[0:1]
	v_mov_b32_e32 v80, v243
	s_add_i32 m0, s20, 0xe000
	s_nop 0
	global_load_lds_dwordx4 v80, s[0:1]
	s_waitcnt vmcnt(8)
	s_waitcnt lgkmcnt(0)
	s_barrier
	s_setprio 1
	s_waitcnt lgkmcnt(0)
	v_mfma_f32_16x16x32_bf16 v[132:135], v[136:139], v[168:171], 0
	v_mfma_f32_16x16x32_bf16 v[128:131], v[144:147], v[168:171], 0
	v_mfma_f32_16x16x32_bf16 v[124:127], v[136:139], v[176:179], 0
	v_mfma_f32_16x16x32_bf16 v[120:123], v[144:147], v[176:179], 0
	v_mfma_f32_16x16x32_bf16 v[108:111], v[136:139], v[184:187], 0
	v_mfma_f32_16x16x32_bf16 v[104:107], v[144:147], v[184:187], 0
	v_mfma_f32_16x16x32_bf16 v[92:95], v[136:139], v[192:195], 0
	v_mfma_f32_16x16x32_bf16 v[86:89], v[144:147], v[192:195], 0
	v_mfma_f32_16x16x32_bf16 v[132:135], v[140:143], v[172:175], v[132:135]
	v_mfma_f32_16x16x32_bf16 v[128:131], v[148:151], v[172:175], v[128:131]
	v_mfma_f32_16x16x32_bf16 v[124:127], v[140:143], v[180:183], v[124:127]
	v_mfma_f32_16x16x32_bf16 v[120:123], v[148:151], v[180:183], v[120:123]
	v_mfma_f32_16x16x32_bf16 v[108:111], v[140:143], v[188:191], v[108:111]
	v_mfma_f32_16x16x32_bf16 v[104:107], v[148:151], v[188:191], v[104:107]
	v_mfma_f32_16x16x32_bf16 v[92:95], v[140:143], v[196:199], v[92:95]
	v_mfma_f32_16x16x32_bf16 v[86:89], v[148:151], v[196:199], v[86:89]
	s_setprio 0
	s_setprio 1
	v_mfma_f32_16x16x32_bf16 v[116:119], v[152:155], v[168:171], 0
	v_mfma_f32_16x16x32_bf16 v[112:115], v[160:163], v[168:171], 0
	v_mfma_f32_16x16x32_bf16 v[100:103], v[152:155], v[176:179], 0
	v_mfma_f32_16x16x32_bf16 v[96:99], v[160:163], v[176:179], 0
	v_mfma_f32_16x16x32_bf16 v[76:79], v[152:155], v[184:187], 0
	v_mfma_f32_16x16x32_bf16 v[72:75], v[160:163], v[184:187], 0
	v_mfma_f32_16x16x32_bf16 v[68:71], v[152:155], v[192:195], 0
	v_mfma_f32_16x16x32_bf16 v[60:63], v[160:163], v[192:195], 0
	v_mfma_f32_16x16x32_bf16 v[116:119], v[156:159], v[172:175], v[116:119]
	v_mfma_f32_16x16x32_bf16 v[112:115], v[164:167], v[172:175], v[112:115]
	v_mfma_f32_16x16x32_bf16 v[100:103], v[156:159], v[180:183], v[100:103]
	v_mfma_f32_16x16x32_bf16 v[96:99], v[164:167], v[180:183], v[96:99]
	v_mfma_f32_16x16x32_bf16 v[76:79], v[156:159], v[188:191], v[76:79]
	v_mfma_f32_16x16x32_bf16 v[72:75], v[164:167], v[188:191], v[72:75]
	v_mfma_f32_16x16x32_bf16 v[68:71], v[156:159], v[196:199], v[68:71]
	v_mfma_f32_16x16x32_bf16 v[60:63], v[164:167], v[196:199], v[60:63]
	s_setprio 0
	s_barrier
	v_mov_b32_e32 v80, v242
	s_add_i32 s0, s34, s23
	ds_read_b128 v[168:171], v246 offset:16384
	ds_read_b128 v[172:175], v246 offset:17408
	ds_read_b128 v[176:179], v246 offset:18432
	ds_read_b128 v[180:183], v246 offset:19456
	ds_read_b128 v[184:187], v246 offset:20480
	ds_read_b128 v[188:191], v246 offset:21504
	ds_read_b128 v[192:195], v246 offset:22528
	ds_read_b128 v[196:199], v246 offset:23552
	s_mov_b32 m0, s0
	s_nop 0
	global_load_lds_dwordx4 v80, s[40:41]
	v_mov_b32_e32 v80, v244
	s_add_i32 m0, s0, 0x2000
	s_add_u32 s0, s40, s74
	global_load_lds_dwordx4 v80, s[40:41]
	s_addc_u32 s1, s41, s75
	v_mov_b32_e32 v80, v242
	s_add_i32 s24, s24, s23
	s_mov_b32 m0, s24
	s_nop 0
	global_load_lds_dwordx4 v80, s[0:1]
	v_mov_b32_e32 v80, v244
	s_add_i32 m0, s24, 0x2000
	s_nop 0
	global_load_lds_dwordx4 v80, s[0:1]
	v_mov_b32_e32 v80, v205
	s_mov_b32 m0, s20
	s_nop 0
	global_load_lds_dwordx4 v80, s[38:39]
	v_mov_b32_e32 v80, v243
	s_mov_b32 m0, s72
	s_nop 0
	global_load_lds_dwordx4 v80, s[38:39]
	s_waitcnt vmcnt(8)
	s_waitcnt lgkmcnt(0)
	s_barrier
	s_setprio 1
	s_waitcnt lgkmcnt(0)
	v_mfma_f32_16x16x32_bf16 v[64:67], v[136:139], v[168:171], 0
	v_mfma_f32_16x16x32_bf16 v[56:59], v[144:147], v[168:171], 0
	v_mfma_f32_16x16x32_bf16 v[52:55], v[136:139], v[176:179], 0
	v_mfma_f32_16x16x32_bf16 v[48:51], v[144:147], v[176:179], 0
	v_mfma_f32_16x16x32_bf16 v[36:39], v[136:139], v[184:187], 0
	v_mfma_f32_16x16x32_bf16 v[32:35], v[144:147], v[184:187], 0
	v_mfma_f32_16x16x32_bf16 v[20:23], v[136:139], v[192:195], 0
	v_mfma_f32_16x16x32_bf16 v[16:19], v[144:147], v[192:195], 0
	v_mfma_f32_16x16x32_bf16 v[64:67], v[140:143], v[172:175], v[64:67]
	v_mfma_f32_16x16x32_bf16 v[56:59], v[148:151], v[172:175], v[56:59]
	v_mfma_f32_16x16x32_bf16 v[52:55], v[140:143], v[180:183], v[52:55]
	v_mfma_f32_16x16x32_bf16 v[48:51], v[148:151], v[180:183], v[48:51]
	v_mfma_f32_16x16x32_bf16 v[36:39], v[140:143], v[188:191], v[36:39]
	v_mfma_f32_16x16x32_bf16 v[32:35], v[148:151], v[188:191], v[32:35]
	v_mfma_f32_16x16x32_bf16 v[20:23], v[140:143], v[196:199], v[20:23]
	v_mfma_f32_16x16x32_bf16 v[16:19], v[148:151], v[196:199], v[16:19]
	s_setprio 0
	s_setprio 1
	v_mfma_f32_16x16x32_bf16 v[44:47], v[152:155], v[168:171], 0
	v_mfma_f32_16x16x32_bf16 v[40:43], v[160:163], v[168:171], 0
	v_mfma_f32_16x16x32_bf16 v[28:31], v[152:155], v[176:179], 0
	v_mfma_f32_16x16x32_bf16 v[24:27], v[160:163], v[176:179], 0
	v_mfma_f32_16x16x32_bf16 v[12:15], v[152:155], v[184:187], 0
	v_mfma_f32_16x16x32_bf16 v[8:11], v[160:163], v[184:187], 0
	v_mfma_f32_16x16x32_bf16 v[4:7], v[152:155], v[192:195], 0
	v_mfma_f32_16x16x32_bf16 v[0:3], v[160:163], v[192:195], 0
	v_mfma_f32_16x16x32_bf16 v[44:47], v[156:159], v[172:175], v[44:47]
	v_mfma_f32_16x16x32_bf16 v[40:43], v[164:167], v[172:175], v[40:43]
	v_mfma_f32_16x16x32_bf16 v[28:31], v[156:159], v[180:183], v[28:31]
	v_mfma_f32_16x16x32_bf16 v[24:27], v[164:167], v[180:183], v[24:27]
	v_mfma_f32_16x16x32_bf16 v[12:15], v[156:159], v[188:191], v[12:15]
	v_mfma_f32_16x16x32_bf16 v[8:11], v[164:167], v[188:191], v[8:11]
	v_mfma_f32_16x16x32_bf16 v[4:7], v[156:159], v[196:199], v[4:7]
	v_mfma_f32_16x16x32_bf16 v[0:3], v[164:167], v[196:199], v[0:3]
	s_setprio 0
	s_barrier
	s_branch .Lp7_ph3
	s_nop 0
	s_nop 0
	s_nop 0
	s_nop 0
	s_nop 0
	s_nop 0
	s_nop 0
	s_nop 0

; #define PG8_MMA(ai, bj, At, Bt) do { __builtin_amdgcn_s_setprio(1); _Pragma("unroll") for (int m = 0; m < 4; ++m) _Pragma("unroll") for (int n = 0; n < 2; ++n) _Pragma("unroll") for (int k = 0; k < 2; ++k) \
;         acc[ai][bj][m][n] = __builtin_amdgcn_mfma_f32_16x16x32_bf16(Bt[n][k], At[m][k], acc[ai][bj][m][n], 0, 0, 0); __builtin_amdgcn_s_setprio(0); } while (0)
; #define PG8_WAIT_V(n) asm volatile("s_waitcnt vmcnt(" #n ")" ::: "memory")
; #define PG8_WAIT_L(n) asm volatile("s_waitcnt lgkmcnt(" #n ")" ::: "memory")
; #define PG8_BAR __builtin_amdgcn_s_barrier()
; #define PG8_SCHED __builtin_amdgcn_sched_barrier(0)
; __device__ __forceinline__ void gemm_phase(LAS unsigned char* lds, const Call& C, const int tid, const Args& args) {
;     ...
;             PG8_WAIT_V(8); PG8_WAIT_L(0); PG8_BAR; PG8_MMA(1, 0, At, B0); PG8_MMA(1, 1, At, B1); PG8_BAR; PG8_SCHED;
;         }
.Lk1_over:
	s_waitcnt vmcnt(8)
	s_waitcnt lgkmcnt(0)
	s_barrier
	s_setprio 1
	s_waitcnt lgkmcnt(0)
	v_mfma_f32_16x16x32_bf16 v[64:67], v[136:139], v[168:171], v[64:67]
	v_mfma_f32_16x16x32_bf16 v[56:59], v[144:147], v[168:171], v[56:59]
	v_mfma_f32_16x16x32_bf16 v[52:55], v[136:139], v[176:179], v[52:55]
	v_mfma_f32_16x16x32_bf16 v[48:51], v[144:147], v[176:179], v[48:51]
	v_mfma_f32_16x16x32_bf16 v[36:39], v[136:139], v[184:187], v[36:39]
	v_mfma_f32_16x16x32_bf16 v[32:35], v[144:147], v[184:187], v[32:35]
	v_mfma_f32_16x16x32_bf16 v[20:23], v[136:139], v[192:195], v[20:23]
	v_mfma_f32_16x16x32_bf16 v[16:19], v[144:147], v[192:195], v[16:19]
	v_mfma_f32_16x16x32_bf16 v[64:67], v[140:143], v[172:175], v[64:67]
	v_mfma_f32_16x16x32_bf16 v[56:59], v[148:151], v[172:175], v[56:59]
	v_mfma_f32_16x16x32_bf16 v[52:55], v[140:143], v[180:183], v[52:55]
	v_mfma_f32_16x16x32_bf16 v[48:51], v[148:151], v[180:183], v[48:51]
	v_mfma_f32_16x16x32_bf16 v[36:39], v[140:143], v[188:191], v[36:39]
	v_mfma_f32_16x16x32_bf16 v[32:35], v[148:151], v[188:191], v[32:35]
	v_mfma_f32_16x16x32_bf16 v[20:23], v[140:143], v[196:199], v[20:23]
	v_mfma_f32_16x16x32_bf16 v[16:19], v[148:151], v[196:199], v[16:19]
	s_setprio 0
	s_setprio 1
	v_mfma_f32_16x16x32_bf16 v[44:47], v[152:155], v[168:171], v[44:47]
	v_mfma_f32_16x16x32_bf16 v[40:43], v[160:163], v[168:171], v[40:43]
	v_mfma_f32_16x16x32_bf16 v[28:31], v[152:155], v[176:179], v[28:31]
	v_mfma_f32_16x16x32_bf16 v[24:27], v[160:163], v[176:179], v[24:27]
	v_mfma_f32_16x16x32_bf16 v[12:15], v[152:155], v[184:187], v[12:15]
	v_mfma_f32_16x16x32_bf16 v[8:11], v[160:163], v[184:187], v[8:11]
	v_mfma_f32_16x16x32_bf16 v[4:7], v[152:155], v[192:195], v[4:7]
	v_mfma_f32_16x16x32_bf16 v[0:3], v[160:163], v[192:195], v[0:3]
	v_mfma_f32_16x16x32_bf16 v[44:47], v[156:159], v[172:175], v[44:47]
	v_mfma_f32_16x16x32_bf16 v[40:43], v[164:167], v[172:175], v[40:43]
	v_mfma_f32_16x16x32_bf16 v[28:31], v[156:159], v[180:183], v[28:31]
	v_mfma_f32_16x16x32_bf16 v[24:27], v[164:167], v[180:183], v[24:27]
	v_mfma_f32_16x16x32_bf16 v[12:15], v[156:159], v[188:191], v[12:15]
	v_mfma_f32_16x16x32_bf16 v[8:11], v[164:167], v[188:191], v[8:11]
	v_mfma_f32_16x16x32_bf16 v[4:7], v[156:159], v[196:199], v[4:7]
	v_mfma_f32_16x16x32_bf16 v[0:3], v[164:167], v[196:199], v[0:3]
	s_setprio 0
	s_add_u32 s16, s16, 0x100
	s_addc_u32 s17, s17, 0
	s_mov_b64 s[0:1], s[8:9]
	s_mov_b32 s24, s25
	s_cmp_ge_u32 s25, s12
	s_barrier
	s_cbranch_scc0 .LBB0_282
	s_branch .Lplc_x
	s_nop 0
	s_nop 0
	s_nop 0
	s_nop 0
	s_nop 0
	s_nop 0
	s_nop 0
.Lplc_x:
	s_and_b64 vcc, exec, s[80:81]
	s_cbranch_vccz .LBB0_285
